# v31 + gMLP epilogue AO stores paired into dwordx4 via v_permlane16_swap (half the store instructions)
# baseline (speedup 1.0000x reference)
; __device__ __forceinline__ unsigned cvt_pk_bf16(float lo, float hi) { unsigned r; asm volatile("v_cvt_pk_bf16_f32 %0, %1, %2" : "=v"(r) : "v"(lo), "v"(hi)); return r; }
; __device__ __forceinline__ float dot4(const f32x4 a) { return (a[0] * a[0] + a[1] * a[1]) + (a[2] * a[2] + a[3] * a[3]); }
; __device__ __forceinline__ float bf2f(unsigned b) { return __uint_as_float(b << 16); }
; __device__ __forceinline__ void gmlp_compute(LAS unsigned char* lds, int gu, const GmlpCur& C, bf16_t* AO, float* partB, int tid) {
;     ...
;     for (int ct = 0; ct < 8; ++ct) { const int col = g * 128 + 16 * ct + 4 * fq; const u32x2 gw = C.gw[ct];
;         f32x4 v; v[0] = bf2f(gw.x & 0xffffu) * (acc[ct][0] + bias); v[1] = bf2f(gw.x >> 16) * (acc[ct][1] + bias); v[2] = bf2f(gw.y & 0xffffu) * (acc[ct][2] + bias); v[3] = bf2f(gw.y >> 16) * (acc[ct][3] + bias);
;         ss += pg8::dot4(v); u32x2 w; w.x = cvt_pk_bf16(v[0], v[1]); w.y = cvt_pk_bf16(v[2], v[3]);
;         *(u32x2*)(AO + (size_t)row * 2048 + 1024 + col) = w; }
.Lgm_w:
	v_pk_add_f32 v[62:63], v[88:89], v[62:63] op_sel_hi:[0,1]
	v_add_u32_e32 v64, s6, v64
	v_pk_mul_f32 v[62:63], v[62:63], v[70:71]
	v_ashrrev_i32_e32 v65, 31, v64
	v_lshlrev_b32_e32 v68, 16, v102
	v_and_b32_e32 v69, 0xffff0000, v102
	v_pk_add_f32 v[60:61], v[88:89], v[60:61] op_sel_hi:[0,1]
	v_mul_f32_e32 v70, v62, v62
	v_or_b32_e32 v74, s34, v80
	v_lshlrev_b64 v[66:67], 12, v[64:65]
	v_pk_mul_f32 v[60:61], v[60:61], v[68:69]
	v_pk_fma_f32 v[70:71], v[62:63], v[62:63], v[70:71] op_sel_hi:[1,1,0]
	v_cvt_pk_bf16_f32 v72, v60, v61
	v_cvt_pk_bf16_f32 v73, v62, v63
	v_lshlrev_b32_e32 v62, 16, v100
	v_and_b32_e32 v63, 0xffff0000, v100
	v_pk_add_f32 v[56:57], v[88:89], v[56:57] op_sel_hi:[0,1]
	v_lshl_add_u64 v[66:67], s[0:1], 0, v[66:67]
	v_mul_f32_e32 v68, v60, v60
	v_lshlrev_b32_e32 v76, 1, v74
	v_pk_mul_f32 v[56:57], v[56:57], v[62:63]
	v_pk_fma_f32 v[68:69], v[60:61], v[60:61], v[68:69] op_sel_hi:[1,1,0]
	v_lshl_add_u64 v[60:61], v[66:67], 0, v[76:77]
	v_and_b32_e32 v176, 16, v212
	v_lshrrev_b32_e32 v177, 1, v176
	v_add_u32_e32 v176, v176, v177
	v_mov_b32_e32 v177, 0
	v_lshl_add_u64 v[178:179], v[60:61], 0, v[176:177]
	v_mul_f32_e32 v62, v56, v56
	v_mov_b32_e32 v160, v72
	v_mov_b32_e32 v161, v73
	v_pk_fma_f32 v[62:63], v[56:57], v[56:57], v[62:63] op_sel_hi:[1,1,0]
	v_lshlrev_b32_e32 v66, 16, v101
	v_and_b32_e32 v67, 0xffff0000, v101
	v_pk_add_f32 v[58:59], v[88:89], v[58:59] op_sel_hi:[0,1]
	v_cvt_pk_bf16_f32 v56, v56, v57
	v_pk_mul_f32 v[58:59], v[58:59], v[66:67]
	v_add_f32_e32 v52, v88, v52
	v_cvt_pk_bf16_f32 v57, v58, v59
	v_mov_b32_e32 v162, v56
	v_mov_b32_e32 v163, v57
	s_nop 1
	v_permlane16_swap_b32_e32 v160, v162
	v_permlane16_swap_b32_e32 v161, v163
	global_store_dwordx4 v[178:179], v[160:163], off offset:2048
	v_lshlrev_b32_e32 v56, 16, v98
	v_mul_f32_e32 v66, v58, v58
	v_mul_f32_e32 v57, v52, v56
	v_and_b32_e32 v52, 0xffff0000, v98
	v_add_f32_e32 v53, v88, v53
	v_pk_fma_f32 v[66:67], v[58:59], v[58:59], v[66:67] op_sel_hi:[1,1,0]
	v_mul_f32_e32 v59, v53, v52
	v_lshlrev_b32_e32 v52, 16, v99
	v_add_f32_e32 v53, v88, v54
	v_mul_f32_e32 v53, v53, v52
	v_and_b32_e32 v52, 0xffff0000, v99
	v_add_f32_e32 v54, v88, v55
	v_mul_f32_e32 v76, v54, v52
	v_cvt_pk_bf16_f32 v54, v57, v59
	v_cvt_pk_bf16_f32 v55, v53, v76
	v_add_f32_e32 v52, v88, v49
	v_lshlrev_b32_e32 v49, 16, v97
	v_add_f32_e32 v50, v88, v50
	v_mov_b32_e32 v164, v54
	v_mov_b32_e32 v165, v55
	v_lshlrev_b32_e32 v54, 16, v96
	v_add_f32_e32 v56, v88, v48
	v_mul_f32_e32 v50, v50, v49
	v_and_b32_e32 v49, 0xffff0000, v97
	v_add_f32_e32 v51, v88, v51
	v_mov_b32_e32 v55, v57
	v_and_b32_e32 v48, 0xffff0000, v96
	v_mul_f32_e32 v58, v51, v49
	v_pk_mul_f32 v[72:73], v[56:57], v[54:55]
	v_mov_b32_e32 v57, v59
	v_mov_b32_e32 v55, v59
	v_mov_b32_e32 v49, v53
	v_pk_mul_f32 v[74:75], v[56:57], v[54:55]
	v_pk_mul_f32 v[96:97], v[52:53], v[48:49]
	v_mov_b32_e32 v53, v76
	v_mov_b32_e32 v49, v76
	v_pk_mul_f32 v[98:99], v[52:53], v[48:49]
	v_pk_mul_f32 v[74:75], v[72:73], v[74:75]
	v_pk_fma_f32 v[54:55], v[56:57], v[54:55], v[72:73]
	v_pk_fma_f32 v[48:49], v[52:53], v[48:49], v[96:97]
	v_mov_b32_e32 v75, v55
	v_pk_mul_f32 v[54:55], v[96:97], v[98:99]
	v_mov_b32_e32 v51, v69
	v_mov_b32_e32 v55, v49
	v_mov_b32_e32 v52, v50
	v_mov_b32_e32 v53, v71
	v_pk_add_f32 v[48:49], v[74:75], v[54:55]
	v_pk_mul_f32 v[52:53], v[50:51], v[52:53]
	v_pk_add_f32 v[54:55], v[68:69], v[70:71]
	v_mov_b32_e32 v59, v63
	v_mov_b32_e32 v53, v55
	v_mov_b32_e32 v54, v58
	v_mov_b32_e32 v55, v67
	v_pk_mul_f32 v[54:55], v[58:59], v[54:55]
	v_pk_add_f32 v[56:57], v[62:63], v[66:67]
	v_lshlrev_b32_e32 v51, 16, v95
	v_mov_b32_e32 v55, v57
	v_pk_add_f32 v[52:53], v[52:53], v[54:55]
	v_pk_add_f32 v[40:41], v[88:89], v[40:41] op_sel_hi:[0,1]
	v_pk_add_f32 v[48:49], v[48:49], v[52:53]
	v_cvt_pk_bf16_f32 v52, v72, v96
	v_cvt_pk_bf16_f32 v53, v50, v58
	v_mov_b32_e32 v166, v52
	v_mov_b32_e32 v167, v53
	s_nop 1
	v_permlane16_swap_b32_e32 v164, v166
	v_permlane16_swap_b32_e32 v165, v167
	global_store_dwordx4 v[178:179], v[164:167], off offset:2112
	v_mov_b32_e32 v52, v44
	v_mov_b32_e32 v53, v46
	v_lshlrev_b32_e32 v50, 16, v94
	v_pk_add_f32 v[52:53], v[88:89], v[52:53] op_sel_hi:[0,1]
	v_mov_b32_e32 v46, v45
	v_pk_mul_f32 v[50:51], v[52:53], v[50:51]
	v_and_b32_e32 v53, 0xffff0000, v95
	v_and_b32_e32 v52, 0xffff0000, v94
	v_pk_add_f32 v[44:45], v[88:89], v[46:47] op_sel_hi:[0,1]
	v_pk_mul_f32 v[44:45], v[44:45], v[52:53]
	v_pk_add_f32 v[42:43], v[88:89], v[42:43] op_sel_hi:[0,1]
	v_pk_mul_f32 v[46:47], v[44:45], v[44:45]
	v_cvt_pk_bf16_f32 v44, v50, v44
	v_cvt_pk_bf16_f32 v45, v51, v45
	v_mov_b32_e32 v168, v44
	v_mov_b32_e32 v169, v45
	v_lshlrev_b32_e32 v44, 16, v92
	v_and_b32_e32 v45, 0xffff0000, v92
	v_pk_mul_f32 v[40:41], v[40:41], v[44:45]
	v_pk_fma_f32 v[46:47], v[50:51], v[50:51], v[46:47]
	v_mul_f32_e32 v44, v40, v40
	v_pk_fma_f32 v[44:45], v[40:41], v[40:41], v[44:45] op_sel_hi:[1,1,0]
	v_lshlrev_b32_e32 v50, 16, v93
	v_and_b32_e32 v51, 0xffff0000, v93
	v_cvt_pk_bf16_f32 v40, v40, v41
	v_pk_mul_f32 v[42:43], v[42:43], v[50:51]
	v_add_f32_e32 v36, v88, v36
	v_cvt_pk_bf16_f32 v41, v42, v43
	v_mov_b32_e32 v170, v40
	v_mov_b32_e32 v171, v41
	s_nop 1
	v_permlane16_swap_b32_e32 v168, v170
	v_permlane16_swap_b32_e32 v169, v171
	global_store_dwordx4 v[178:179], v[168:171], off offset:2176
	v_lshlrev_b32_e32 v40, 16, v90
	v_mul_f32_e32 v41, v36, v40
	v_and_b32_e32 v36, 0xffff0000, v90
	v_add_f32_e32 v37, v88, v37
	v_mul_f32_e32 v53, v37, v36
	v_lshlrev_b32_e32 v36, 16, v91
	v_add_f32_e32 v37, v88, v38
	v_mul_f32_e32 v37, v37, v36
	v_and_b32_e32 v36, 0xffff0000, v91
	v_add_f32_e32 v38, v88, v39
	v_mul_f32_e32 v50, v42, v42
; __device__ __forceinline__ unsigned cvt_pk_bf16(float lo, float hi) { unsigned r; asm volatile("v_cvt_pk_bf16_f32 %0, %1, %2" : "=v"(r) : "v"(lo), "v"(hi)); return r; }
; __device__ __forceinline__ float dot4(const f32x4 a) { return (a[0] * a[0] + a[1] * a[1]) + (a[2] * a[2] + a[3] * a[3]); }
; #define LAS __attribute__((address_space(3)))
; __device__ __forceinline__ float bf2f(unsigned b) { return __uint_as_float(b << 16); }
; __device__ __forceinline__ void gmlp_store_lds(const GmlpIn& R, LAS unsigned char* lds, int tid) {
; #pragma unroll
;     for (int it = 0; it < 2; ++it) { const int task = it * NTHREADS + tid, cc = task & 15, p = task >> 4;
;         const f32x4 pa = R.pa[it], pb = R.pb[it];
;         const float rsa = __builtin_amdgcn_rsqf(((pa[0] + pa[1]) + (pa[2] + pa[3])) * (1.0f / 128.0f) + EPS), rsb = __builtin_amdgcn_rsqf(((pb[0] + pb[1]) + (pb[2] + pb[3])) * (1.0f / 128.0f) + EPS);
; #pragma unroll
;         for (int i = 0; i < 4; ++i) { const unsigned wa = R.a[it][i], wb = R.b[it][i];
;             *(LAS unsigned*)(lds + (cc * 8 + 2 * i) * GT_STRIDE + p * 4) = cvt_pk_bf16(bf2f(wa & 0xffffu) * rsa, bf2f(wb & 0xffffu) * rsb);
;             *(LAS unsigned*)(lds + (cc * 8 + 2 * i + 1) * GT_STRIDE + p * 4) = cvt_pk_bf16(bf2f(wa >> 16) * rsa, bf2f(wb >> 16) * rsb); } }
; }
; __device__ __forceinline__ void gmlp_compute(LAS unsigned char* lds, int gu, const GmlpCur& C, bf16_t* AO, float* partB, int tid) {
;     ...
;     for (int ct = 0; ct < 8; ++ct) { const int col = g * 128 + 16 * ct + 4 * fq; const u32x2 gw = C.gw[ct];
;         f32x4 v; v[0] = bf2f(gw.x & 0xffffu) * (acc[ct][0] + bias); v[1] = bf2f(gw.x >> 16) * (acc[ct][1] + bias); v[2] = bf2f(gw.y & 0xffffu) * (acc[ct][2] + bias); v[3] = bf2f(gw.y >> 16) * (acc[ct][3] + bias);
;         ss += pg8::dot4(v); u32x2 w; w.x = cvt_pk_bf16(v[0], v[1]); w.y = cvt_pk_bf16(v[2], v[3]);
;         *(u32x2*)(AO + (size_t)row * 2048 + 1024 + col) = w; }
;     ss += __shfl_xor(ss, 16); ss += __shfl_xor(ss, 32);
;     partB[(size_t)row * 8 + g] = ss;
	v_mul_f32_e32 v62, v38, v36
	v_add_f32_e32 v36, v88, v33
	v_lshlrev_b32_e32 v33, 16, v87
	v_add_f32_e32 v34, v88, v34
	v_pk_fma_f32 v[50:51], v[42:43], v[42:43], v[50:51] op_sel_hi:[1,1,0]
	v_lshlrev_b32_e32 v42, 16, v86
	v_add_f32_e32 v40, v88, v32
	v_mul_f32_e32 v34, v34, v33
	v_and_b32_e32 v33, 0xffff0000, v87
	v_add_f32_e32 v35, v88, v35
	v_mov_b32_e32 v43, v41
	v_cvt_pk_bf16_f32 v38, v41, v53
	v_and_b32_e32 v32, 0xffff0000, v86
	v_mul_f32_e32 v52, v35, v33
	v_pk_mul_f32 v[54:55], v[40:41], v[42:43]
	v_mov_b32_e32 v41, v53
	v_mov_b32_e32 v43, v53
	v_mov_b32_e32 v33, v37
	v_cvt_pk_bf16_f32 v39, v37, v62
	v_pk_mul_f32 v[56:57], v[40:41], v[42:43]
	v_pk_mul_f32 v[58:59], v[36:37], v[32:33]
	v_mov_b32_e32 v37, v62
	v_mov_b32_e32 v33, v62
	v_pk_mul_f32 v[62:63], v[36:37], v[32:33]
	v_pk_mul_f32 v[56:57], v[54:55], v[56:57]
	v_pk_fma_f32 v[40:41], v[40:41], v[42:43], v[54:55]
	v_pk_fma_f32 v[32:33], v[36:37], v[32:33], v[58:59]
	v_mov_b32_e32 v57, v41
	v_pk_mul_f32 v[40:41], v[58:59], v[62:63]
	v_mov_b32_e32 v35, v45
	v_mov_b32_e32 v41, v33
	v_mov_b32_e32 v36, v34
	v_mov_b32_e32 v37, v51
	v_pk_add_f32 v[48:49], v[48:49], v[48:49] op_sel_hi:[0,1]
	v_pk_add_f32 v[46:47], v[46:47], v[46:47] op_sel_hi:[0,1]
	v_pk_add_f32 v[32:33], v[56:57], v[40:41]
	v_pk_mul_f32 v[36:37], v[34:35], v[36:37]
	v_pk_add_f32 v[40:41], v[44:45], v[50:51]
	v_mov_b32_e32 v53, v47
	v_mov_b32_e32 v37, v41
	v_mov_b32_e32 v40, v52
	v_mov_b32_e32 v41, v49
	v_pk_mul_f32 v[40:41], v[52:53], v[40:41]
	v_pk_add_f32 v[42:43], v[46:47], v[48:49]
	v_and_b32_e32 v35, 64, v112
	v_mov_b32_e32 v41, v43
	v_pk_add_f32 v[36:37], v[36:37], v[40:41]
	v_add_u32_e32 v35, 64, v35
	v_pk_add_f32 v[32:33], v[32:33], v[36:37]
	v_mov_b32_e32 v172, v38
	v_mov_b32_e32 v173, v39
	v_add_f32_e32 v32, v32, v33
	v_xor_b32_e32 v33, 16, v112
	v_cmp_lt_i32_e32 vcc, v33, v35
	s_lshl_b32 s6, s19, 2
	s_xor_b32 s13, s13, 1
	v_cndmask_b32_e32 v33, v112, v33, vcc
	v_lshlrev_b32_e32 v33, 2, v33
	ds_bpermute_b32 v33, v33, v32
	s_waitcnt lgkmcnt(0)
	v_add_f32_e32 v36, v32, v33
	v_xor_b32_e32 v32, 32, v112
	v_cmp_lt_i32_e32 vcc, v32, v35
	s_nop 1
	v_cndmask_b32_e32 v32, v112, v32, vcc
	v_lshlrev_b32_e32 v32, 2, v32
	ds_bpermute_b32 v35, v32, v36
	v_cvt_pk_bf16_f32 v32, v54, v58
	v_cvt_pk_bf16_f32 v33, v34, v52
	v_mov_b32_e32 v174, v32
	v_mov_b32_e32 v175, v33
	s_nop 1
	v_permlane16_swap_b32_e32 v172, v174
	v_permlane16_swap_b32_e32 v173, v175
	global_store_dwordx4 v[178:179], v[172:175], off offset:2240
	v_lshlrev_b64 v[32:33], 5, v[64:65]
	v_lshl_add_u64 v[32:33], s[36:37], 0, v[32:33]
	s_waitcnt lgkmcnt(0)
	v_add_f32_e32 v34, v36, v35
	v_lshl_add_u64 v[32:33], v[32:33], 0, s[6:7]
	s_andn2_b64 vcc, exec, s[10:11]
	global_store_dword v[32:33], v34, off
	s_cbranch_vccnz .LBB0_569
	s_waitcnt vmcnt(5)
	v_add_f32_e32 v32, v8, v9
	v_add_f32_e32 v33, v10, v11
	v_add_f32_e32 v32, v32, v33
	v_add_f32_e32 v33, v12, v13
	v_add_f32_e32 v34, v14, v15
	v_add_f32_e32 v33, v33, v34
	v_fmamk_f32 v32, v32, 0x3c000000, v111
	v_fmamk_f32 v33, v33, 0x3c000000, v111
	v_rsq_f32_e32 v32, v32
	v_rsq_f32_e32 v33, v33
	v_lshlrev_b32_e32 v34, 16, v0
	v_lshlrev_b32_e32 v35, 16, v4
	s_mul_i32 s6, s13, 0x8800
	v_mul_f32_e32 v34, v32, v34
	v_mul_f32_e32 v35, v33, v35
	v_cvt_pk_bf16_f32 v34, v34, v35
	v_add_u32_e32 v35, s6, v108
	v_add_u32_e32 v36, v35, v107
	ds_write_b32 v36, v34
	v_and_b32_e32 v34, 0xffff0000, v0
	v_mul_f32_e32 v34, v32, v34
	v_and_b32_e32 v37, 0xffff0000, v4
	v_mul_f32_e32 v37, v33, v37
	v_cvt_pk_bf16_f32 v34, v34, v37
	ds_write_b32 v36, v34 offset:272
	v_lshlrev_b32_e32 v34, 16, v1
	v_mul_f32_e32 v34, v32, v34
	v_lshlrev_b32_e32 v37, 16, v5
	v_mul_f32_e32 v37, v33, v37
	v_cvt_pk_bf16_f32 v34, v34, v37
	ds_write_b32 v36, v34 offset:544
	v_and_b32_e32 v34, 0xffff0000, v1
	v_mul_f32_e32 v34, v32, v34
	v_and_b32_e32 v37, 0xffff0000, v5
	v_mul_f32_e32 v37, v33, v37
	v_cvt_pk_bf16_f32 v34, v34, v37
	ds_write_b32 v36, v34 offset:816
	v_lshlrev_b32_e32 v34, 16, v2
	v_mul_f32_e32 v34, v32, v34
	v_lshlrev_b32_e32 v37, 16, v6
	v_mul_f32_e32 v37, v33, v37
	v_cvt_pk_bf16_f32 v34, v34, v37
	ds_write_b32 v36, v34 offset:1088
	v_and_b32_e32 v34, 0xffff0000, v2
	v_mul_f32_e32 v34, v32, v34
	v_and_b32_e32 v37, 0xffff0000, v6
	v_mul_f32_e32 v37, v33, v37
	v_cvt_pk_bf16_f32 v34, v34, v37
	ds_write_b32 v36, v34 offset:1360
	v_lshlrev_b32_e32 v34, 16, v3
	v_mul_f32_e32 v34, v32, v34
	v_lshlrev_b32_e32 v37, 16, v7
	v_mul_f32_e32 v37, v33, v37
	v_cvt_pk_bf16_f32 v34, v34, v37
	ds_write_b32 v36, v34 offset:1632
	v_and_b32_e32 v34, 0xffff0000, v3
	v_mul_f32_e32 v32, v32, v34
	v_and_b32_e32 v34, 0xffff0000, v7
	v_mul_f32_e32 v33, v33, v34
	v_cvt_pk_bf16_f32 v32, v32, v33
	ds_write_b32 v36, v32 offset:1904
	v_add_f32_e32 v32, v24, v25
	v_add_f32_e32 v33, v26, v27
	v_add_f32_e32 v32, v32, v33
	v_add_f32_e32 v33, v28, v29
	v_add_f32_e32 v34, v30, v31
	v_fmamk_f32 v32, v32, 0x3c000000, v111
	v_add_f32_e32 v33, v33, v34
	v_rsq_f32_e32 v32, v32
	v_fmamk_f32 v33, v33, 0x3c000000, v111
	v_rsq_f32_e32 v33, v33
	v_lshlrev_b32_e32 v34, 16, v16
	v_mul_f32_e32 v34, v32, v34
	v_lshlrev_b32_e32 v36, 16, v20
	v_mul_f32_e32 v36, v33, v36
	v_cvt_pk_bf16_f32 v34, v34, v36
	v_add_u32_e32 v35, v35, v109
	ds_write_b32 v35, v34
	v_and_b32_e32 v34, 0xffff0000, v16
	v_mul_f32_e32 v34, v32, v34
	v_and_b32_e32 v36, 0xffff0000, v20
	v_mul_f32_e32 v36, v33, v36
	v_cvt_pk_bf16_f32 v34, v34, v36
	ds_write_b32 v35, v34 offset:272
	v_lshlrev_b32_e32 v34, 16, v17
	v_mul_f32_e32 v34, v32, v34
	v_lshlrev_b32_e32 v36, 16, v21
	v_mul_f32_e32 v36, v33, v36
	v_cvt_pk_bf16_f32 v34, v34, v36
	ds_write_b32 v35, v34 offset:544
	v_and_b32_e32 v34, 0xffff0000, v17
	v_mul_f32_e32 v34, v32, v34
	v_and_b32_e32 v36, 0xffff0000, v21
	v_mul_f32_e32 v36, v33, v36
	v_cvt_pk_bf16_f32 v34, v34, v36
	ds_write_b32 v35, v34 offset:816
	v_lshlrev_b32_e32 v34, 16, v18
	v_mul_f32_e32 v34, v32, v34
	v_lshlrev_b32_e32 v36, 16, v22
	v_mul_f32_e32 v36, v33, v36
	v_cvt_pk_bf16_f32 v34, v34, v36
	ds_write_b32 v35, v34 offset:1088
	v_and_b32_e32 v34, 0xffff0000, v18
	v_mul_f32_e32 v34, v32, v34
	v_and_b32_e32 v36, 0xffff0000, v22
	v_mul_f32_e32 v36, v33, v36
	v_cvt_pk_bf16_f32 v34, v34, v36
	ds_write_b32 v35, v34 offset:1360
	v_lshlrev_b32_e32 v34, 16, v19
	v_mul_f32_e32 v34, v32, v34
	v_lshlrev_b32_e32 v36, 16, v23
	v_mul_f32_e32 v36, v33, v36
	v_cvt_pk_bf16_f32 v34, v34, v36
	ds_write_b32 v35, v34 offset:1632
	v_and_b32_e32 v34, 0xffff0000, v19
	v_mul_f32_e32 v32, v32, v34
	v_and_b32_e32 v34, 0xffff0000, v23
	v_mul_f32_e32 v33, v33, v34
	v_cvt_pk_bf16_f32 v32, v32, v33
	ds_write_b32 v35, v32 offset:1904
	s_branch .LBB0_569
